# P1 unit header: generic division by the band height (always 8 for 128 row blocks) replaced by a shift: 27 dependent scalar/VALU instructions fewer before every unit
# speedup vs baseline: 1.0080x; 1.0004x over previous
;     __host__ __device__ bool next(int i, Unit& u) const {
;         const long L = (long)i * G + c; if (L >= nwg) return false;
;         int wgid = (int)L; { const int q = nwg / NXCD, r = nwg % NXCD, xcd = wgid % NXCD, off = wgid / NXCD; wgid = (xcd < r ? xcd * (q + 1) : r * (q + 1) + (xcd - r) * q) + off; }
;         const int nig = WGM * nN, gid = wgid / nig, fm = gid * WGM, gsz = (nM - fm) < WGM ? (nM - fm) : WGM;
;         u.pm = fm + ((wgid % nig) % gsz); u.pn = (wgid % nig) / gsz + ((gid & 1) ? rot : 0); if (u.pn >= nN) u.pn -= nN; return true;
.LBB0_140:
	s_add_i32 s0, s0, 1
	s_mul_i32 s1, s0, s33
	s_mul_hi_u32 s8, s0, s3
	s_add_i32 s8, s8, s1
	s_mul_i32 s1, s0, s3
	s_add_u32 s84, s1, s96
	s_addc_u32 s85, s8, s6
	v_cmp_gt_i64_e32 vcc, s[84:85], v[164:165]
	v_cmp_lt_i64_e64 s[8:9], s[84:85], v[160:161]
	s_cbranch_vccnz .LBB0_142
	s_ashr_i32 s1, s84, 31
	s_lshr_b32 s1, s1, 29
	s_add_i32 s1, s84, s1
	s_ashr_i32 s11, s1, 3
	s_and_b32 s1, s1, -8
	s_sub_i32 s1, s84, s1
	s_cmp_lt_i32 s1, 0
	s_movk_i32 s79, 0x181
	s_cselect_b32 s79, s79, 0x180
	s_mul_i32 s1, s1, s79
	s_add_i32 s1, s1, s11
	s_mul_hi_i32 s11, s1, 0x2aaaaaab
	s_lshr_b32 s79, s11, 31
	s_ashr_i32 s11, s11, 5
	s_add_i32 s11, s11, s79
	s_lshl_b32 s79, s11, 3
	s_sub_i32 s80, 0x80, s79
	s_min_i32 s80, s80, 8
	s_mul_i32 s82, s11, 0xc0
	s_sub_i32 s1, s1, s82
	s_ashr_i32 s81, s1, 3
	s_mul_i32 s80, s81, s80
	s_sub_i32 s1, s1, s80
	s_add_i32 s80, s79, s1
	s_lshl_b32 s1, s11, 1
	s_and_b32 s1, s1, 2
	s_add_i32 s1, s1, s81
	s_cmp_lt_i32 s1, 24
	s_cselect_b32 s11, 0, 0xffffffe8
	s_add_i32 s82, s11, s1
